# start-up hand-off wait, XCD post and census deferred behind P0
# speedup vs baseline: 1.0026x; 1.0026x over previous
; #define LAS __attribute__((address_space(3)))
; __device__ __forceinline__ void p0_prologue(const Args& a, LAS unsigned char* lds, int gw, int NGW, int wave, int lane) {
;     ...
;     for (int it = gw; it < NITEMS; it += NGW) {
;         int r = it;
;         if (r < 2 * I_GU) {
;             const bool second = r >= I_GU; if (second) r -= I_GU;
;             const int nblk = NGU / 32, kb = r / nblk, nb = r % nblk, n = nb * 32 + (lane & 31);
;             const float* wg = second ? a.w2g : a.w1g; const float* wu = second ? a.w2u : a.w1u;
;             const float* colp = (((n >> 7) & 1) ? wu : wg) + 128 * (n >> 8) + (n & 127);
;             transpose_item(colp, DFF, second ? a.g2 : a.g1, (bf16_t*)(ws + (second ? WS_W2GU : WS_W1GU)), DM, 0, kb * 64, nb * 32, scr, lane);
; __global__ void __launch_bounds__(NWAVES * 64, 2) fwd_megakernel(Args args) {
;     ...
;     if (tid < 4) ((LAS unsigned*)(lds + LDS_BARW))[tid] = 0u;
;     for (unsigned i = (unsigned)(bx * (NWAVES * 64) + tid); i < (unsigned)(CTL_USED_BYTES / 16); i += (unsigned)(G * NWAVES * 64)) ((u32x4*)(ws + WS_CTL))[i] = (u32x4){0u, 0u, 0u, 0u};
;     grid.sync();
;     const XcdBarrier xbar = xcd_barrier_post((unsigned*)(ws + WS_CTL), (volatile LAS unsigned*)(lds + LDS_BARW));
;     unsigned* xl = (unsigned*)(ws + WS_XL);
;     const int myx = (int)(xbar.x & 7u);
;     if (tid == 0) ((LAS unsigned*)(lds + LDS_BARW))[4] = __hip_atomic_fetch_add(xl + 64 * myx, 1u, __ATOMIC_RELAXED, __HIP_MEMORY_SCOPE_AGENT);
;     __syncthreads();
;     const int myrank = (int)((volatile LAS unsigned*)(lds + LDS_BARW))[4];
.LBB0_15:
	s_or_b64 exec, exec, s[0:1]
	s_getreg_b32 s0, hwreg(HW_REG_XCC_ID, 0, 4)
	s_and_b32 s93, s0, 15
	v_cmp_eq_u32_e64 s[90:91], 0, v153
	s_add_u32 s26, s74, 0xc800
	s_addc_u32 s27, s75, 0
	s_and_b32 s92, s0, 7
	s_lshr_b32 s78, s96, 6
	s_lshl_b32 s46, s95, 3
	s_add_u32 s24, s74, 0x10000
	s_addc_u32 s25, s75, 0
	s_cmp_lt_i32 s88, 1
	s_cselect_b64 s[0:1], -1, 0
	s_cmp_gt_i32 s89, 0
	s_cselect_b64 s[2:3], -1, 0
	s_and_b64 s[28:29], s[0:1], s[2:3]
	v_and_b32_e32 v152, 63, v153
	s_andn2_b64 vcc, exec, s[28:29]
	v_writelane_b32 v245, s80, 1
	s_nop 1
	v_writelane_b32 v245, s81, 2
	v_writelane_b32 v245, s82, 3
	v_writelane_b32 v245, s83, 4
	v_writelane_b32 v245, s84, 5
	v_writelane_b32 v245, s85, 6
	v_writelane_b32 v245, s86, 7
	v_writelane_b32 v245, s87, 8
	v_writelane_b32 v245, s78, 9
	s_cbranch_vccnz .LBB0_489
	s_add_i32 s4, s78, s46
	s_lshl_b32 s0, s76, 3
	s_cmpk_gt_i32 s4, 0x2dff
	s_cbranch_scc1 .LBB0_436
	v_lshlrev_b32_e32 v1, 3, v153
	v_readlane_b32 s36, v245, 9
	v_and_b32_e32 v2, 56, v1
	s_lshl_b32 s1, s36, 14
	v_lshrrev_b32_e32 v32, 3, v152
	v_mov_b32_e32 v5, 0
	v_lshlrev_b32_e32 v4, 1, v2
	s_add_i32 s1, s1, 0
	v_lshrrev_b32_e32 v0, 5, v152
	v_mul_u32_u24_e32 v1, 0x84, v2
	v_lshl_add_u64 v[8:9], s[74:75], 0, v[4:5]
	v_lshlrev_b32_e32 v4, 2, v32
	s_movk_i32 s6, 0x84
	v_add3_u32 v33, s1, v1, v4
	v_or_b32_e32 v1, 2, v0
	v_mov_b32_e32 v4, 0x108
	v_mad_u32_u24 v38, v1, s6, v4
	v_mov_b32_e32 v4, 0x318
	v_mad_u32_u24 v39, v1, s6, v4
	v_mov_b32_e32 v4, 0x528
	v_mad_u32_u24 v40, v1, s6, v4
	v_mov_b32_e32 v4, 0x738
	v_and_b32_e32 v3, 31, v153
	v_mad_u32_u24 v41, v1, s6, v4
	v_mov_b32_e32 v4, 0x948
	v_lshl_add_u32 v30, v3, 2, s1
	s_add_u32 s1, s74, 0x1b00000
	v_mad_u32_u24 v42, v1, s6, v4
	v_mov_b32_e32 v4, 0xb58
	s_addc_u32 s5, s75, 0
	v_mad_u32_u24 v43, v1, s6, v4
	v_mov_b32_e32 v4, 0xd68
	s_mov_b64 s[2:3], 0x1d00000
	v_mad_u32_u24 v44, v1, s6, v4
	v_mov_b32_e32 v4, 0xf78
	s_cmp_lg_u64 s[68:69], 0
	v_lshl_add_u64 v[6:7], v[8:9], 0, s[2:3]
	v_mad_u32_u24 v45, v1, s6, v4
	v_mov_b32_e32 v4, 0x1188
	s_mov_b64 s[2:3], 0x1200000
	s_cselect_b64 s[30:31], -1, 0
	s_cmp_eq_u64 s[22:23], 0
	v_mad_u32_u24 v46, v1, s6, v4
	v_mov_b32_e32 v4, 0x1398
	v_lshl_add_u64 v[8:9], v[8:9], 0, s[2:3]
	s_cselect_b64 s[2:3], -1, 0
	s_cmp_lg_u64 s[20:21], 0
	v_mad_u32_u24 v31, v0, s6, v30
	v_mad_u32_u24 v47, v1, s6, v4
	s_cselect_b64 s[34:35], -1, 0
	s_lshl_b32 s6, s95, 8
	s_lshl_b32 s33, s36, 5
	s_add_i32 s33, s6, s33
	s_lshl_b32 s6, s95, 4
	s_lshl_b32 s36, s36, 1
	s_mov_b32 s7, 0
	v_or_b32_e32 v34, 8, v32
	v_or_b32_e32 v35, 16, v32
	v_or_b32_e32 v36, 24, v32
	v_mul_u32_u24_e32 v37, 0x84, v1
	v_mov_b32_e32 v1, v5
	s_lshl_b32 s47, s76, 8
	s_add_i32 s78, s6, s36
	s_lshl_b32 s79, s76, 4
	v_cndmask_b32_e64 v48, 0, 1, s[30:31]
	s_movk_i32 s80, 0xd500
	s_movk_i32 s81, 0x1108
	s_movk_i32 s82, 0x908
	s_xor_b64 s[36:37], s[2:3], -1
	s_movk_i32 s83, 0xe480
	s_mov_b32 s84, 0x2a00000
	s_movk_i32 s85, 0x2c00
	s_mov_b32 s86, 0x1f00000
	s_mov_b32 s87, s4
	s_branch .LBB0_27

; #define LAS __attribute__((address_space(3)))
; __global__ void __launch_bounds__(NWAVES * 64, 2) fwd_megakernel(Args args) {
;     ...
;     const XcdBarrier xbar = xcd_barrier_post((unsigned*)(ws + WS_CTL), (volatile LAS unsigned*)(lds + LDS_BARW));
;     unsigned* xl = (unsigned*)(ws + WS_XL);
;     const int myx = (int)(xbar.x & 7u);
;     if (tid == 0) ((LAS unsigned*)(lds + LDS_BARW))[4] = __hip_atomic_fetch_add(xl + 64 * myx, 1u, __ATOMIC_RELAXED, __HIP_MEMORY_SCOPE_AGENT);
;     __syncthreads();
;     const int myrank = (int)((volatile LAS unsigned*)(lds + LDS_BARW))[4];
.LBB0_489:
	s_and_saveexec_b64 s[0:1], s[90:91]
	s_cbranch_execz .Ldf_1
	s_cmp_lg_u32 s95, 0
	s_cbranch_scc0 .Ldf_acq
	v_mov_b32_e32 v2, 0

; #define LAS __attribute__((address_space(3)))
; #define SEAM(k) do { if (IN(k) && IN((k) + 1)) xcd_barrier(xbar); } while (0)
; __global__ void __launch_bounds__(NWAVES * 64, 2) fwd_megakernel(Args args) {
;     ...
;     const XcdBarrier xbar = xcd_barrier_post((unsigned*)(ws + WS_CTL), (volatile LAS unsigned*)(lds + LDS_BARW));
;     unsigned* xl = (unsigned*)(ws + WS_XL);
;     const int myx = (int)(xbar.x & 7u);
;     if (tid == 0) ((LAS unsigned*)(lds + LDS_BARW))[4] = __hip_atomic_fetch_add(xl + 64 * myx, 1u, __ATOMIC_RELAXED, __HIP_MEMORY_SCOPE_AGENT);
;     __syncthreads();
;     const int myrank = (int)((volatile LAS unsigned*)(lds + LDS_BARW))[4];
;     ...
;     if (IN(0)) { p0_prologue(args, lds, gw, NGW, wave, lane); }
;     SEAM(0);
.Ldf_1:
	s_or_b64 exec, exec, s[0:1]
	s_barrier
	s_and_saveexec_b64 s[2:3], s[90:91]
	s_cbranch_execz .Ldf_2
	s_lshl_b32 s1, s93, 8
	v_mov_b32_e32 v0, s1
	v_mov_b32_e32 v1, 1
	global_atomic_add v0, v1, s[74:75] offset:1024
	s_lshl_b32 s0, s92, 8
	v_mov_b32_e32 v1, s0
	v_mov_b32_e32 v2, 1
	global_atomic_add v1, v1, v2, s[26:27] sc0
	s_waitcnt vmcnt(0)
	v_mov_b32_e32 v0, 0x23fd0
	ds_write_b32 v0, v1
.Ldf_2:
	s_or_b64 exec, exec, s[2:3]
	v_mov_b32_e32 v0, 0x23fd0
	s_waitcnt lgkmcnt(0)
	s_barrier
	ds_read_b32 v0, v0
	s_waitcnt lgkmcnt(0)
	v_readfirstlane_b32 s0, v0
	s_nop 3
	v_writelane_b32 v245, s0, 0
	s_cmp_gt_i32 s89, 1
	s_cselect_b64 s[2:3], -1, 0
	s_and_b64 s[0:1], s[28:29], s[2:3]
	s_andn2_b64 vcc, exec, s[0:1]
	s_cbranch_vccnz .LBB0_543
	s_waitcnt vmcnt(0)
	s_barrier
	s_and_saveexec_b64 s[4:5], s[90:91]
	s_cbranch_execz .LBB0_542
	s_add_i32 s0, 0, 0x23fc0
	s_waitcnt vmcnt(4)
	v_mov_b32_e32 v0, s0
	s_waitcnt vmcnt(0) expcnt(0) lgkmcnt(0)
	ds_read_b32 v2, v0
	s_add_i32 s0, 0, 0x23fc4
	v_mov_b32_e32 v0, s0
	ds_read_b32 v0, v0
	s_waitcnt lgkmcnt(1)
	v_cmp_ne_u32_e32 vcc, 0, v2
	s_cbranch_vccnz .LBB0_506
	s_add_u32 s6, s74, 0x1000
	s_addc_u32 s7, s75, 0
	s_add_u32 s8, s74, 0x1100
	s_addc_u32 s9, s75, 0
	s_add_u32 s10, s74, 0x1200
	s_addc_u32 s11, s75, 0
	s_mul_i32 s0, s77, s94
	s_add_u32 s12, s74, 0x1300
	s_mul_i32 s0, s0, s76
	s_addc_u32 s13, s75, 0
	s_mov_b32 s1, 1
	v_mov_b32_e32 v16, 0
	s_branch .LBB0_494
